# P0 role split 4 streaming waves + 4 transposing waves instead of 2 + 6
# baseline (speedup 1.0000x reference)
; #define LAS __attribute__((address_space(3)))
; __device__ __forceinline__ void p0_prologue(const Args& a, LAS unsigned char* lds, int wave, int lane) {
;     if (wave < 6) {
;         LAS float* scr = (LAS float*)(lds + wave * 16384);
;         const int gw = blockIdx.x * 6 + wave, NGW = gridDim.x * 6;
;         const float* w_in = a.in[3]; const float* w_oa = a.in[10]; const float* w_ob = a.in[11]; const float* w_o = a.in[12]; const float* ng = a.in[2];
;         bf16_t* WIN = (bf16_t*)(a.ws + WS_WIN); bf16_t* WAB = (bf16_t*)(a.ws + WS_WAB); bf16_t* WO = (bf16_t*)(a.ws + WS_WO);
;         constexpr int I_IN = 16 * 168, I_OA = 8 * 32, I_OB = 8 * 32, I_O = 16 * 32, NITEMS = I_IN + I_OA + I_OB + I_O;
;         for (int it = gw; it < NITEMS; it += NGW) {
;             int r = it;
;             if (r < I_IN) { const int kb = r / 168, nb = r % 168; p0_transpose_item(w_in, NIN, 64 * kb, map_col(32 * nb), ng, WIN, 32 * nb, 64 * kb, scr, lane); continue; } r -= I_IN;
;             if (r < I_OA) { const int kb = r / 32, nb = r % 32; p0_transpose_item(w_oa, 1024, 64 * kb, 32 * nb, nullptr, WAB, 32 * nb, 64 * kb, scr, lane); continue; } r -= I_OA;
;             if (r < I_OB) { const int kb = r / 32, nb = r % 32; p0_transpose_item(w_ob, 1024, 64 * kb, 32 * nb, nullptr, WAB, 32 * nb, 512 + 64 * kb, scr, lane); continue; } r -= I_OB;
;             { const int kb = r / 32, nb = r % 32; p0_transpose_item(w_o, 1024, 64 * kb, 32 * nb, nullptr, WO, 32 * nb, 64 * kb, scr, lane); }
;         }
;     } else {
;         bf16_t* XB = (bf16_t*)(a.ws + WS_XB);
;         const int gw = blockIdx.x * 2 + (wave - 6), NGW = gridDim.x * 2;
;         f32x4 va[4][4], vb[4][4];
;         int m0 = gw;
;         if (m0 < T) p0_load4(a, m0, NGW, lane, va);
.Lxcc_noor:
	s_movk_i32 s32, 0xa7f
	s_lshr_b32 s3, s48, 6
	s_cmp_lt_i32 s66, 1
	s_cselect_b64 s[0:1], -1, 0
	s_cmp_gt_i32 s67, 0
	s_cselect_b64 s[4:5], -1, 0
	s_and_b64 s[4:5], s[0:1], s[4:5]
	s_andn2_b64 vcc, exec, s[4:5]
	v_and_b32_e32 v191, 63, v190
	s_cbranch_vccnz .LBB0_106
	s_cmpk_gt_u32 s48, 0xff
	s_mov_b64 s[0:1], -1
	s_cbranch_scc0 .LBB0_41
	s_load_dword s6, s[74:75], 0x80
	s_lshl_b32 s12, s2, 2
	s_add_i32 s10, s12, s3
	s_add_i32 s10, s10, -4
	s_cmp_lt_i32 s10, 0x4000
	s_waitcnt lgkmcnt(0)
	s_mul_i32 s6, s6, 2
	s_mul_i32 s8, s6, 6
	s_cbranch_scc1 .LBB0_21
	s_lshl_b32 s7, s6, 2
	s_mul_i32 s9, s6, 6
	s_mov_b64 s[0:1], 0
	s_andn2_b64 vcc, exec, s[0:1]
	v_lshlrev_b32_e32 v130, 4, v191
	s_cbranch_vccnz .LBB0_23
	s_branch .LBB0_22

; __device__ __forceinline__ void p0_prologue(const Args& a, LAS unsigned char* lds, int wave, int lane) {
;     ...
;         const int gw = blockIdx.x * 2 + (wave - 6), NGW = gridDim.x * 2;
;         f32x4 va[4][4], vb[4][4];
;         int m0 = gw;
;         if (m0 < T) p0_load4(a, m0, NGW, lane, va);
;         while (m0 < T) {
;             const int m1 = m0 + 4 * NGW; const bool has1 = m1 < T;
;             if (has1) p0_load4(a, m1, NGW, lane, vb);
;             p0_proc4(XB, m0, NGW, lane, va);
;             if (!has1) break;
;             const int m2 = m1 + 4 * NGW; const bool has2 = m2 < T;
;             if (has2) p0_load4(a, m2, NGW, lane, va);
;             p0_proc4(XB, m1, NGW, lane, vb);
;             if (!has2) break;
;             m0 = m2;
;         }
.LBB0_23:
	v_lshlrev_b32_e32 v64, 3, v191
	v_mov_b32_e32 v65, 0
	v_lshl_add_u64 v[64:65], s[64:65], 0, v[64:65]
	s_mov_b64 s[0:1], 0x1100000
	v_lshl_add_u64 v[128:129], v[64:65], 0, s[0:1]
	s_lshl_b32 s0, s6, 1
	s_add_i32 s13, s0, s12
	s_mul_i32 s0, s6, 10
	s_add_i32 s15, s0, s12
	s_mul_i32 s0, s6, 18
	s_add_i32 s17, s0, s12
	s_mul_i32 s0, s6, 20
	s_add_i32 s18, s0, s12
	s_mul_i32 s0, s6, 22
	s_add_i32 s19, s0, s12
	s_mul_i32 s0, s6, 12
	s_add_i32 s21, s0, s12
	s_mul_i32 s0, s6, 14
	s_lshl_b32 s20, s6, 3
	s_lshl_b32 s14, s6, 4
	s_add_i32 s22, s0, s12
	s_add_i32 s23, s7, s12
	s_add_i32 s24, s9, s12
	v_mbcnt_lo_u32_b32 v64, -1, 0
	s_add_i32 s13, s13, -4
	s_add_i32 s15, s15, -4
	s_add_i32 s16, s14, s12
	s_add_i32 s17, s17, -4
	s_add_i32 s18, s18, -4
	s_add_i32 s19, s19, -4
	s_add_i32 s20, s20, s12
	s_add_i32 s21, s21, -4
	s_add_i32 s22, s22, -4
	s_add_i32 s23, s23, -4
	s_add_i32 s24, s24, -4
	v_mov_b32_e32 v131, 0x358637bd
	s_mov_b32 s25, 0xf800000
	v_mov_b32_e32 v132, 0x260
	v_mbcnt_hi_u32_b32 v133, -1, v64
	s_mov_b32 s26, s3
	s_branch .LBB0_26
.LBB0_24:
	s_add_i32 s26, s26, s14
	s_add_i32 s0, s12, s26
	s_add_i32 s0, s0, -4
	s_cmp_gt_i32 s0, 0x3fff
	s_cselect_b64 s[0:1], -1, 0

; __device__ __forceinline__ void p0_load4(const Args& a, int m0, int NGW, int lane, f32x4 (&v)[4][4]) {
; #pragma unroll
;     for (int u = 0; u < 4; ++u) { const int m = min(m0 + u * NGW, T - 1);
;         const float* xrow = m < TP ? a.in[0] + (size_t)m * 1024 : a.in[1] + (size_t)(m - TP) * 1024;
;         const f32x4* xr = (const f32x4*)xrow + lane;
; #pragma unroll
;         for (int j = 0; j < 4; ++j) v[u][j] = xr[64 * j]; }
; }
; __device__ __forceinline__ void p0_prologue(const Args& a, LAS unsigned char* lds, int wave, int lane) {
;     ...
;         while (m0 < T) {
;             const int m1 = m0 + 4 * NGW; const bool has1 = m1 < T;
;             if (has1) p0_load4(a, m1, NGW, lane, vb);
.LBB0_26:
	s_add_i32 s0, s12, s26
	s_add_i32 s10, s0, -4
	s_cmp_gt_i32 s10, 0x3fff
	s_mov_b64 s[0:1], -1
	s_cbranch_scc1 .LBB0_25
	s_add_i32 s0, s20, s26
	s_add_i32 s6, s0, -4
	s_cmp_lt_i32 s6, 0x4000
	s_cselect_b64 s[8:9], -1, 0
	s_cmp_gt_i32 s6, 0x3fff
	s_cbranch_scc1 .LBB0_29
	s_add_i32 s0, s0, 0xffff7ffc
	s_ashr_i32 s1, s6, 31
	s_cmp_lt_i32 s6, 0x8000
	s_cselect_b32 s1, s1, 0
	s_cselect_b32 s0, s6, s0
	s_cselect_b32 s7, s77, s79
	s_cselect_b32 s11, s76, s78
	s_lshl_b64 s[0:1], s[0:1], 12
	s_add_u32 s0, s11, s0
	s_addc_u32 s1, s7, s1
	global_load_dwordx4 v[76:79], v130, s[0:1]
	global_load_dwordx4 v[72:75], v130, s[0:1] offset:1024
	global_load_dwordx4 v[68:71], v130, s[0:1] offset:2048
	global_load_dwordx4 v[64:67], v130, s[0:1] offset:3072
	s_add_i32 s0, s15, s26
	s_min_i32 s7, s0, 0x3fff
	s_ashr_i32 s1, s7, 31
	s_add_i32 s11, s7, 0xffff8000
	s_cmp_lt_i32 s0, 0x8000
	s_cselect_b32 s1, s1, 0
	s_cselect_b32 s0, s7, s11
	s_cselect_b32 s7, s77, s79
	s_cselect_b32 s11, s76, s78
	s_lshl_b64 s[0:1], s[0:1], 12
	s_add_u32 s0, s11, s0
	s_addc_u32 s1, s7, s1
	global_load_dwordx4 v[92:95], v130, s[0:1]
	global_load_dwordx4 v[88:91], v130, s[0:1] offset:1024
	global_load_dwordx4 v[84:87], v130, s[0:1] offset:2048
	global_load_dwordx4 v[80:83], v130, s[0:1] offset:3072
	s_add_i32 s0, s21, s26
	s_min_i32 s7, s0, 0x3fff
	s_ashr_i32 s1, s7, 31
	s_add_i32 s11, s7, 0xffff8000
	s_cmp_lt_i32 s0, 0x8000
	s_cselect_b32 s1, s1, 0
	s_cselect_b32 s0, s7, s11
	s_cselect_b32 s7, s77, s79
	s_cselect_b32 s11, s76, s78
	s_lshl_b64 s[0:1], s[0:1], 12
	s_add_u32 s0, s11, s0
	s_addc_u32 s1, s7, s1
	global_load_dwordx4 v[108:111], v130, s[0:1]
	global_load_dwordx4 v[104:107], v130, s[0:1] offset:1024
	global_load_dwordx4 v[100:103], v130, s[0:1] offset:2048
	global_load_dwordx4 v[96:99], v130, s[0:1] offset:3072
	s_add_i32 s0, s22, s26
	s_min_i32 s7, s0, 0x3fff
	s_ashr_i32 s1, s7, 31
	s_add_i32 s11, s7, 0xffff8000
	s_cmp_lt_i32 s0, 0x8000
	s_cselect_b32 s1, s1, 0
	s_cselect_b32 s0, s7, s11
	s_cselect_b32 s7, s77, s79
	s_cselect_b32 s11, s76, s78
	s_lshl_b64 s[0:1], s[0:1], 12
	s_add_u32 s0, s11, s0
	s_addc_u32 s1, s7, s1
	global_load_dwordx4 v[124:127], v130, s[0:1]
	global_load_dwordx4 v[120:123], v130, s[0:1] offset:1024
	global_load_dwordx4 v[116:119], v130, s[0:1] offset:2048
	global_load_dwordx4 v[112:115], v130, s[0:1] offset:3072
	s_waitcnt vmcnt(16) lgkmcnt(0)
	v_pk_mul_f32 v[134:135], v[2:3], v[2:3]
	v_pk_mul_f32 v[136:137], v[0:1], v[0:1]
	s_branch .Lxs_29go

; __device__ __forceinline__ void p0_load4(const Args& a, int m0, int NGW, int lane, f32x4 (&v)[4][4]) {
; #pragma unroll
;     for (int u = 0; u < 4; ++u) { const int m = min(m0 + u * NGW, T - 1);
;         const float* xrow = m < TP ? a.in[0] + (size_t)m * 1024 : a.in[1] + (size_t)(m - TP) * 1024;
;         const f32x4* xr = (const f32x4*)xrow + lane;
; #pragma unroll
;         for (int j = 0; j < 4; ++j) v[u][j] = xr[64 * j]; }
; }
; __device__ __forceinline__ void p0_prologue(const Args& a, LAS unsigned char* lds, int wave, int lane) {
;     ...
;             const int m2 = m1 + 4 * NGW; const bool has2 = m2 < T;
;             if (has2) p0_load4(a, m2, NGW, lane, va);
.LBB0_33:
	s_andn2_b64 vcc, exec, s[8:9]
	s_mov_b64 s[0:1], -1
	s_cbranch_vccnz .LBB0_25
	s_add_i32 s1, s16, s26
	s_add_i32 s0, s1, -4
	s_cmp_gt_i32 s0, 0x3fff
	s_cbranch_scc1 .Lxs_skip36
	s_add_i32 s7, s1, 0xffff7ffc
	s_ashr_i32 s1, s0, 31
	s_cmp_lt_i32 s0, 0x8000
	s_cselect_b32 s1, s1, 0
	s_cselect_b32 s0, s0, s7
	s_cselect_b32 s7, s77, s79
	s_cselect_b32 s8, s76, s78
	s_lshl_b64 s[0:1], s[0:1], 12
	s_add_u32 s0, s8, s0
	s_addc_u32 s1, s7, s1
	global_load_dwordx4 v[0:3], v130, s[0:1]
	global_load_dwordx4 v[4:7], v130, s[0:1] offset:1024
	global_load_dwordx4 v[8:11], v130, s[0:1] offset:2048
	global_load_dwordx4 v[12:15], v130, s[0:1] offset:3072
	s_add_i32 s0, s17, s26
	s_min_i32 s7, s0, 0x3fff
	s_ashr_i32 s1, s7, 31
	s_add_i32 s8, s7, 0xffff8000
	s_cmp_lt_i32 s0, 0x8000
	s_cselect_b32 s1, s1, 0
	s_cselect_b32 s0, s7, s8
	s_cselect_b32 s7, s77, s79
	s_cselect_b32 s8, s76, s78
	s_lshl_b64 s[0:1], s[0:1], 12
	s_add_u32 s0, s8, s0
	s_addc_u32 s1, s7, s1
	global_load_dwordx4 v[16:19], v130, s[0:1]
	global_load_dwordx4 v[20:23], v130, s[0:1] offset:1024
	global_load_dwordx4 v[24:27], v130, s[0:1] offset:2048
	global_load_dwordx4 v[28:31], v130, s[0:1] offset:3072
	s_add_i32 s0, s18, s26
	s_min_i32 s7, s0, 0x3fff
	s_ashr_i32 s1, s7, 31
	s_add_i32 s8, s7, 0xffff8000
	s_cmp_lt_i32 s0, 0x8000
	s_cselect_b32 s1, s1, 0
	s_cselect_b32 s0, s7, s8
	s_cselect_b32 s7, s77, s79
	s_cselect_b32 s8, s76, s78
	s_lshl_b64 s[0:1], s[0:1], 12
	s_add_u32 s0, s8, s0
	s_addc_u32 s1, s7, s1
	global_load_dwordx4 v[32:35], v130, s[0:1]
	global_load_dwordx4 v[36:39], v130, s[0:1] offset:1024
	global_load_dwordx4 v[40:43], v130, s[0:1] offset:2048
	global_load_dwordx4 v[44:47], v130, s[0:1] offset:3072
	s_add_i32 s0, s19, s26
	s_min_i32 s7, s0, 0x3fff
	s_ashr_i32 s1, s7, 31
	s_add_i32 s8, s7, 0xffff8000
	s_cmp_lt_i32 s0, 0x8000
	s_cselect_b32 s1, s1, 0
	s_cselect_b32 s0, s7, s8
	s_cselect_b32 s7, s77, s79
	s_cselect_b32 s8, s76, s78
	s_lshl_b64 s[0:1], s[0:1], 12
	s_add_u32 s0, s8, s0
	s_addc_u32 s1, s7, s1
	global_load_dwordx4 v[48:51], v130, s[0:1]
	global_load_dwordx4 v[52:55], v130, s[0:1] offset:1024
	global_load_dwordx4 v[56:59], v130, s[0:1] offset:2048
	global_load_dwordx4 v[60:63], v130, s[0:1] offset:3072
	s_waitcnt vmcnt(16)

; #define LAS __attribute__((address_space(3)))
; __device__ __forceinline__ void p0_transpose_item(const float* W, int N, int ksrc0, int nsrc0, const float* ksc, bf16_t* WT, int nrow0, int kdst0, LAS float* scr, int lane) {
; #pragma unroll 8
;     for (int i = 0; i < 32; ++i) { const int kk = 2 * i + (lane >> 5); float v = W[(size_t)(ksrc0 + kk) * N + nsrc0 + (lane & 31)]; if (ksc) v *= ksc[ksrc0 + kk]; scr[kk * 33 + (lane & 31)] = v; }
; __device__ __forceinline__ void p0_prologue(const Args& a, LAS unsigned char* lds, int wave, int lane) {
;     if (wave < 6) {
;         LAS float* scr = (LAS float*)(lds + wave * 16384);
;         const int gw = blockIdx.x * 6 + wave, NGW = gridDim.x * 6;
;         const float* w_in = a.in[3]; const float* w_oa = a.in[10]; const float* w_ob = a.in[11]; const float* w_o = a.in[12]; const float* ng = a.in[2];
;         bf16_t* WIN = (bf16_t*)(a.ws + WS_WIN); bf16_t* WAB = (bf16_t*)(a.ws + WS_WAB); bf16_t* WO = (bf16_t*)(a.ws + WS_WO);
;         constexpr int I_IN = 16 * 168, I_OA = 8 * 32, I_OB = 8 * 32, I_O = 16 * 32, NITEMS = I_IN + I_OA + I_OB + I_O;
;         for (int it = gw; it < NITEMS; it += NGW) {
;             int r = it;
;             if (r < I_IN) { const int kb = r / 168, nb = r % 168; p0_transpose_item(w_in, NIN, 64 * kb, map_col(32 * nb), ng, WIN, 32 * nb, 64 * kb, scr, lane); continue; } r -= I_IN;
;             if (r < I_OA) { const int kb = r / 32, nb = r % 32; p0_transpose_item(w_oa, 1024, 64 * kb, 32 * nb, nullptr, WAB, 32 * nb, 64 * kb, scr, lane); continue; } r -= I_OA;
;             if (r < I_OB) { const int kb = r / 32, nb = r % 32; p0_transpose_item(w_ob, 1024, 64 * kb, 32 * nb, nullptr, WAB, 32 * nb, 512 + 64 * kb, scr, lane); continue; } r -= I_OB;
;             { const int kb = r / 32, nb = r % 32; p0_transpose_item(w_o, 1024, 64 * kb, 32 * nb, nullptr, WO, 32 * nb, 64 * kb, scr, lane); }
.LBB0_41:
	s_and_b64 vcc, exec, s[0:1]
	s_cbranch_vccz .LBB0_106
	s_mul_i32 s0, s2, 4
	s_add_i32 s20, s3, s0
	s_cmp_gt_i32 s20, s32
	s_cbranch_scc1 .Lp0t_exit
.Llate_entry:
	s_load_dword s21, s[74:75], 0x80
	s_waitcnt vmcnt(15)
	v_and_b32_e32 v1, 31, v190
	s_load_dwordx8 s[12:19], s[74:75], 0x40
	s_add_u32 s6, s64, 0xb00000
	v_lshlrev_b32_e32 v2, 2, v1
	v_lshlrev_b32_e32 v1, 3, v190
	s_addc_u32 s7, s65, 0
	s_lshl_b32 s8, s3, 14
	v_lshrrev_b32_e32 v0, 5, v191
	v_mov_b32_e32 v3, 0
	s_waitcnt vmcnt(10)
	v_and_b32_e32 v20, 56, v1
	s_add_i32 s10, s8, 0
	v_lshrrev_b32_e32 v7, 3, v191
	v_lshlrev_b32_e32 v16, 1, v20
	v_mov_b32_e32 v17, v3
	v_mul_u32_u24_e32 v18, 0x84, v0
	v_mul_u32_u24_e32 v1, 0x84, v20
	v_lshl_add_u64 v[8:9], s[64:65], 0, v[16:17]
	s_mov_b64 s[0:1], 0xd00000
	v_lshlrev_b32_e32 v12, 2, v7
	s_waitcnt lgkmcnt(0)
	s_cmp_lg_u64 s[80:81], 0
	v_or_b32_e32 v18, s8, v18
	s_movk_i32 s12, 0xd600
	s_mov_b32 s9, 0
	s_mul_i32 s21, s21, 4
	v_lshl_add_u64 v[4:5], s[60:61], 0, v[2:3]
	v_add_u32_e32 v6, s10, v2
	s_movk_i32 s22, 0x84
	v_lshl_add_u64 v[10:11], v[8:9], 0, s[0:1]
	s_waitcnt vmcnt(4)
	v_add3_u32 v44, s10, v1, v12
	v_or_b32_e32 v45, 8, v7
	v_or_b32_e32 v46, 16, v7
	v_or_b32_e32 v47, 24, v7
	v_lshl_add_u64 v[12:13], s[18:19], 0, v[2:3]
	v_lshl_add_u64 v[14:15], s[16:17], 0, v[2:3]
	v_lshl_add_u64 v[16:17], s[6:7], 0, v[16:17]
	s_cselect_b64 s[10:11], -1, 0
	v_mov_b32_e32 v1, v0
	s_waitcnt vmcnt(3)
	v_add3_u32 v48, v18, v2, 0
	v_lshl_add_u64 v[18:19], s[82:83], 0, v[2:3]
	v_or_b32_e32 v49, 14, v0
	v_or_b32_e32 v50, 12, v0
	v_or_b32_e32 v51, 10, v0
	s_waitcnt vmcnt(2)
	v_or_b32_e32 v52, 8, v0
	v_or_b32_e32 v53, 6, v0
	v_or_b32_e32 v54, 4, v0
	v_or_b32_e32 v55, 2, v0
	v_lshlrev_b32_e32 v20, 1, v20
	s_mov_b32 s13, -1
	s_movk_i32 s23, 0xd00
	s_movk_i32 s24, 0x5400
	s_cmpk_eq_u32 s32, 0xe7f
	s_cselect_b32 s21, 0x200, s21
	s_branch .LBB0_46
